# P5a: sum-of-squares loads issued inside the K loop (every iteration, counted by the next DMA wait); epilogue starts without waiting for the last 8 DMA loads
# baseline (speedup 1.0000x reference)
; #define PG8_STAGE(bufoff, gbase, voff) do { _Pragma("unroll") for (int _i = 0; _i < 2; ++_i) \
;         __builtin_amdgcn_global_load_lds((const unsigned*)((const char*)(gbase) + (voff)[_i]), (PG8_LAS unsigned*)(lds + (bufoff) + ldsw + _i * 8192), 16, 0, 0); } while (0)
; #define PG8_LDA(dst, b, h) do { _Pragma("unroll") for (int m = 0; m < 4; ++m) _Pragma("unroll") for (int k = 0; k < 2; ++k) dst[m][k] = *(const PG8_LAS bf16x8*)(lds + PG8_SA(b, h) + aoff + m * 2048 + k * 1024); } while (0)
; #define PG8_LDB(dst, b, h) do { _Pragma("unroll") for (int n = 0; n < 2; ++n) _Pragma("unroll") for (int k = 0; k < 2; ++k) dst[n][k] = *(const PG8_LAS bf16x8*)(lds + PG8_SB(b, h) + boff + n * 2048 + k * 1024); } while (0)
; #define PG8_WAIT_V(n) asm volatile("s_waitcnt vmcnt(" #n ")" ::: "memory")
; #define PG8_WAIT_L(n) asm volatile("s_waitcnt lgkmcnt(" #n ")" ::: "memory")
; #define PG8_BAR __builtin_amdgcn_s_barrier()
; #define PG8_SCHED __builtin_amdgcn_sched_barrier(0)
; template <class Epi, class Sched, bool ALIGN_EPI = false, bool SP2 = false>
; __device__ __forceinline__ void gemm_phase(PG8_LAS unsigned char* lds, const Gemm g, const Sched& S, const Epi& E) {
;     ...
;         const bool has_next = S.next(ui + 1, nxt);
;         const char* nA = has_next ? (const char*)g.A + (size_t)nxt.pm * tstep : cA; const char* nB = has_next ? (const char*)g.Bt + (size_t)nxt.pn * tstep : cB;
;         for (int t = 0; t < nt; t += 2) {
;             const bool last = (t == nt - 2);
;             const char* a1 = cA + (size_t)(t + 1) * kstep;
;             const char* a2 = last ? nA : cA + (size_t)(t + 2) * kstep; const char* b2 = last ? nB : cB + (size_t)(t + 2) * kstep;
;             const char* a3 = a2 + kstep; const char* b3 = b2 + kstep;
;             if (last && has_next) S.a_ready(nxt);
;             if constexpr (SP2) {
;             PG8_LDB(B0, 0, 0); PG8_LDB(B1, 0, 1); PG8_SCHED; PG8_LDA(At, 0, 0); PG8_STAGE(PG8_SA(1, 1), a1 + hstep, voffA);
;             PG8_WAIT_V(8); PG8_WAIT_L(0); PG8_BAR; PG8_MMA(0, 0, At, B0); PG8_MMA(0, 1, At, B1); PG8_BAR; PG8_SCHED;
;     ...
; #pragma unroll
;         for (int a = 0; a < 2; ++a)
; #pragma unroll
;             for (int b = 0; b < 2; ++b)
; #pragma unroll
;                 for (int m = 0; m < 4; ++m)
; #pragma unroll
;                     for (int n = 0; n < 2; ++n) acc[a][b][m][n] = (f32x4){0.f, 0.f, 0.f, 0.f};
.LBB0_489:
	s_lshl_b32 s30, s24, 8
	s_add_i32 s30, s30, s48
	v_or_b32_e32 v254, s30, v162
	v_ashrrev_i32_e32 v255, 31, v254
	v_lshl_add_u64 v[254:255], v[254:255], 2, s[8:9]
	s_ashr_i32 s19, s18, 31
	s_lshl_b64 s[20:21], s[18:19], 19
	s_add_u32 s20, s34, s20
	s_addc_u32 s21, s35, s21
	s_and_b64 s[22:23], s[2:3], exec
	s_cselect_b32 s5, s21, s27
	s_cselect_b32 s19, s20, s26
	s_ashr_i32 s17, s16, 31
	s_lshl_b64 s[22:23], s[16:17], 19
	s_add_u32 s22, s36, s22
	s_addc_u32 s23, s37, s23
	s_and_b64 s[30:31], s[2:3], exec
	s_cselect_b32 s17, s23, s29
	s_cselect_b32 s25, s22, s28
	s_add_u32 s26, s26, 0x40080
	s_addc_u32 s27, s27, 0
	s_add_u32 s76, s28, 0x100
	v_mov_b32_e32 v0, 0
	s_addc_u32 s77, s29, 0
	s_mov_b32 s78, -2
	v_mov_b32_e32 v1, v0
	v_mov_b32_e32 v2, v0
	v_mov_b32_e32 v3, v0
	v_mov_b32_e32 v4, v0
	v_mov_b32_e32 v5, v0
	v_mov_b32_e32 v6, v0
	v_mov_b32_e32 v7, v0
	v_mov_b32_e32 v16, v0
	v_mov_b32_e32 v17, v0
	v_mov_b32_e32 v18, v0
	v_mov_b32_e32 v19, v0
	v_mov_b32_e32 v20, v0
	v_mov_b32_e32 v21, v0
	v_mov_b32_e32 v22, v0
	v_mov_b32_e32 v23, v0
	v_mov_b32_e32 v32, v0
	v_mov_b32_e32 v33, v0
	v_mov_b32_e32 v34, v0
	v_mov_b32_e32 v35, v0
	v_mov_b32_e32 v36, v0
	v_mov_b32_e32 v37, v0
	v_mov_b32_e32 v38, v0
	v_mov_b32_e32 v39, v0
	v_mov_b32_e32 v48, v0
	v_mov_b32_e32 v49, v0
	v_mov_b32_e32 v50, v0
	v_mov_b32_e32 v51, v0
	v_mov_b32_e32 v52, v0
	v_mov_b32_e32 v53, v0
	v_mov_b32_e32 v54, v0
	v_mov_b32_e32 v55, v0
	v_mov_b32_e32 v8, v0
	v_mov_b32_e32 v9, v0
	v_mov_b32_e32 v10, v0
	v_mov_b32_e32 v11, v0
	v_mov_b32_e32 v12, v0
	v_mov_b32_e32 v13, v0
	v_mov_b32_e32 v14, v0
	v_mov_b32_e32 v15, v0
	v_mov_b32_e32 v24, v0
	v_mov_b32_e32 v25, v0
	v_mov_b32_e32 v26, v0
	v_mov_b32_e32 v27, v0
	v_mov_b32_e32 v28, v0
	v_mov_b32_e32 v29, v0
	v_mov_b32_e32 v30, v0
	v_mov_b32_e32 v31, v0
	v_mov_b32_e32 v40, v0
	v_mov_b32_e32 v41, v0
	v_mov_b32_e32 v42, v0
	v_mov_b32_e32 v43, v0
	v_mov_b32_e32 v44, v0
	v_mov_b32_e32 v45, v0
	v_mov_b32_e32 v46, v0
	v_mov_b32_e32 v47, v0
	v_mov_b32_e32 v56, v0
	v_mov_b32_e32 v57, v0
	v_mov_b32_e32 v58, v0
	v_mov_b32_e32 v59, v0
	v_mov_b32_e32 v60, v0
	v_mov_b32_e32 v61, v0
	v_mov_b32_e32 v62, v0
	v_mov_b32_e32 v63, v0
	v_mov_b32_e32 v64, v0
	v_mov_b32_e32 v65, v0
	v_mov_b32_e32 v66, v0
	v_mov_b32_e32 v67, v0
	v_mov_b32_e32 v68, v0
	v_mov_b32_e32 v69, v0
	v_mov_b32_e32 v70, v0
	v_mov_b32_e32 v71, v0
	v_mov_b32_e32 v80, v0
	v_mov_b32_e32 v81, v0
	v_mov_b32_e32 v82, v0
	v_mov_b32_e32 v83, v0
	v_mov_b32_e32 v84, v0
	v_mov_b32_e32 v85, v0
	v_mov_b32_e32 v86, v0
	v_mov_b32_e32 v87, v0
	v_mov_b32_e32 v96, v0
	v_mov_b32_e32 v97, v0
	v_mov_b32_e32 v98, v0
	v_mov_b32_e32 v99, v0
	v_mov_b32_e32 v100, v0
	v_mov_b32_e32 v101, v0
	v_mov_b32_e32 v102, v0
	v_mov_b32_e32 v103, v0
	v_mov_b32_e32 v112, v0
	v_mov_b32_e32 v113, v0
	v_mov_b32_e32 v114, v0
	v_mov_b32_e32 v115, v0
	v_mov_b32_e32 v116, v0
	v_mov_b32_e32 v117, v0
	v_mov_b32_e32 v118, v0
	v_mov_b32_e32 v119, v0
	v_mov_b32_e32 v72, v0
	v_mov_b32_e32 v73, v0
	v_mov_b32_e32 v74, v0
	v_mov_b32_e32 v75, v0
	v_mov_b32_e32 v76, v0
	v_mov_b32_e32 v77, v0
	v_mov_b32_e32 v78, v0
	v_mov_b32_e32 v79, v0
	v_mov_b32_e32 v88, v0
	v_mov_b32_e32 v89, v0
	v_mov_b32_e32 v90, v0
	v_mov_b32_e32 v91, v0
	v_mov_b32_e32 v92, v0
	v_mov_b32_e32 v93, v0
	v_mov_b32_e32 v94, v0
	v_mov_b32_e32 v95, v0
	v_mov_b32_e32 v104, v0
	v_mov_b32_e32 v105, v0
	v_mov_b32_e32 v106, v0
	v_mov_b32_e32 v107, v0
	v_mov_b32_e32 v108, v0
	v_mov_b32_e32 v109, v0
	v_mov_b32_e32 v110, v0
	v_mov_b32_e32 v111, v0
	v_mov_b32_e32 v120, v0
	v_mov_b32_e32 v121, v0
	v_mov_b32_e32 v122, v0
	v_mov_b32_e32 v123, v0
	v_mov_b32_e32 v124, v0
	v_mov_b32_e32 v125, v0
	v_mov_b32_e32 v126, v0
	v_mov_b32_e32 v127, v0
.LBB0_490:
	ds_read_b128 v[144:147], v161
	ds_read_b128 v[168:171], v161 offset:1024
	ds_read_b128 v[172:175], v161 offset:2048
	ds_read_b128 v[176:179], v161 offset:3072
	ds_read_b128 v[180:183], v163
	ds_read_b128 v[188:191], v163 offset:1024
	ds_read_b128 v[192:195], v163 offset:2048
	ds_read_b128 v[196:199], v163 offset:3072
	s_add_u32 s28, s26, 0xfffc0080
	s_addc_u32 s29, s27, -1
	s_cmp_eq_u32 s78, 12
	s_cselect_b32 s31, s5, s29
	s_cselect_b32 s30, s19, s28
	s_cselect_b32 s29, s17, s77
	s_cselect_b32 s28, s25, s76
	v_lshl_add_u64 v[148:149], s[26:27], 0, v[136:137]
	s_add_i32 m0, s39, 0xc000
	ds_read_b128 v[200:203], v164
	ds_read_b128 v[204:207], v164 offset:1024
	ds_read_b128 v[208:211], v164 offset:2048
	ds_read_b128 v[212:215], v164 offset:3072
	ds_read_b128 v[216:219], v164 offset:4096
	ds_read_b128 v[220:223], v164 offset:5120
	ds_read_b128 v[224:227], v164 offset:6144
	ds_read_b128 v[228:231], v164 offset:7168
	global_load_lds_dwordx4 v[148:149], off
	v_lshl_add_u64 v[148:149], s[26:27], 0, v[138:139]
	s_add_i32 m0, s39, 0xe000
	s_nop 0
	global_load_lds_dwordx4 v[148:149], off
	s_waitcnt vmcnt(8)
	s_waitcnt lgkmcnt(0)
	s_barrier
; #define PG8_STAGE(bufoff, gbase, voff) do { _Pragma("unroll") for (int _i = 0; _i < 2; ++_i) \
;         __builtin_amdgcn_global_load_lds((const unsigned*)((const char*)(gbase) + (voff)[_i]), (PG8_LAS unsigned*)(lds + (bufoff) + ldsw + _i * 8192), 16, 0, 0); } while (0)
; #define PG8_LDA(dst, b, h) do { _Pragma("unroll") for (int m = 0; m < 4; ++m) _Pragma("unroll") for (int k = 0; k < 2; ++k) dst[m][k] = *(const PG8_LAS bf16x8*)(lds + PG8_SA(b, h) + aoff + m * 2048 + k * 1024); } while (0)
; #define PG8_MMA(ai, bj, At, Bt) do { __builtin_amdgcn_s_setprio(1); _Pragma("unroll") for (int m = 0; m < 4; ++m) _Pragma("unroll") for (int n = 0; n < 2; ++n) _Pragma("unroll") for (int k = 0; k < 2; ++k) \
;         acc[ai][bj][m][n] = __builtin_amdgcn_mfma_f32_16x16x32_bf16(Bt[n][k], At[m][k], acc[ai][bj][m][n], 0, 0, 0); __builtin_amdgcn_s_setprio(0); } while (0)
; #define PG8_WAIT_V(n) asm volatile("s_waitcnt vmcnt(" #n ")" ::: "memory")
; #define PG8_WAIT_L(n) asm volatile("s_waitcnt lgkmcnt(" #n ")" ::: "memory")
; #define PG8_BAR __builtin_amdgcn_s_barrier()
; #define PG8_SCHED __builtin_amdgcn_sched_barrier(0)
; template <class Epi, class Sched, bool ALIGN_EPI = false, bool SP2 = false>
; __device__ __forceinline__ void gemm_phase(PG8_LAS unsigned char* lds, const Gemm g, const Sched& S, const Epi& E) {
;     ...
;             PG8_WAIT_V(8); PG8_WAIT_L(0); PG8_BAR; PG8_MMA(0, 0, At, B0); PG8_MMA(0, 1, At, B1); PG8_BAR; PG8_SCHED;
;             PG8_LDA(At, 0, 1); PG8_STAGE(PG8_SB(0, 0), b2, voffB); PG8_STAGE(PG8_SB(0, 1), b2 + hstep, voffB); PG8_STAGE(PG8_SA(0, 0), a2, voffA);
;             PG8_WAIT_V(8); PG8_WAIT_L(0); PG8_BAR; PG8_MMA(1, 0, At, B0); PG8_MMA(1, 1, At, B1); PG8_BAR; PG8_SCHED;
	s_setprio 1
	s_waitcnt lgkmcnt(0)
	v_mfma_f32_16x16x32_bf16 v[124:127], v[144:147], v[200:203], v[124:127]
	v_mfma_f32_16x16x32_bf16 v[120:123], v[172:175], v[200:203], v[120:123]
	v_mfma_f32_16x16x32_bf16 v[108:111], v[144:147], v[208:211], v[108:111]
	v_mfma_f32_16x16x32_bf16 v[104:107], v[172:175], v[208:211], v[104:107]
	v_mfma_f32_16x16x32_bf16 v[92:95], v[144:147], v[216:219], v[92:95]
	v_mfma_f32_16x16x32_bf16 v[88:91], v[172:175], v[216:219], v[88:91]
	v_mfma_f32_16x16x32_bf16 v[76:79], v[144:147], v[224:227], v[76:79]
	v_mfma_f32_16x16x32_bf16 v[72:75], v[172:175], v[224:227], v[72:75]
	v_mfma_f32_16x16x32_bf16 v[124:127], v[168:171], v[204:207], v[124:127]
	v_mfma_f32_16x16x32_bf16 v[120:123], v[176:179], v[204:207], v[120:123]
	v_mfma_f32_16x16x32_bf16 v[108:111], v[168:171], v[212:215], v[108:111]
	v_mfma_f32_16x16x32_bf16 v[104:107], v[176:179], v[212:215], v[104:107]
	v_mfma_f32_16x16x32_bf16 v[92:95], v[168:171], v[220:223], v[92:95]
	v_mfma_f32_16x16x32_bf16 v[88:91], v[176:179], v[220:223], v[88:91]
	v_mfma_f32_16x16x32_bf16 v[76:79], v[168:171], v[228:231], v[76:79]
	v_mfma_f32_16x16x32_bf16 v[72:75], v[176:179], v[228:231], v[72:75]
	s_setprio 0
	s_setprio 1
	v_mfma_f32_16x16x32_bf16 v[116:119], v[180:183], v[200:203], v[116:119]
	v_mfma_f32_16x16x32_bf16 v[112:115], v[192:195], v[200:203], v[112:115]
	v_mfma_f32_16x16x32_bf16 v[100:103], v[180:183], v[208:211], v[100:103]
	v_mfma_f32_16x16x32_bf16 v[96:99], v[192:195], v[208:211], v[96:99]
	v_mfma_f32_16x16x32_bf16 v[84:87], v[180:183], v[216:219], v[84:87]
	v_mfma_f32_16x16x32_bf16 v[80:83], v[192:195], v[216:219], v[80:83]
	v_mfma_f32_16x16x32_bf16 v[68:71], v[180:183], v[224:227], v[68:71]
	v_mfma_f32_16x16x32_bf16 v[64:67], v[192:195], v[224:227], v[64:67]
	v_mfma_f32_16x16x32_bf16 v[116:119], v[188:191], v[204:207], v[116:119]
	v_mfma_f32_16x16x32_bf16 v[112:115], v[196:199], v[204:207], v[112:115]
	v_mfma_f32_16x16x32_bf16 v[100:103], v[188:191], v[212:215], v[100:103]
	v_mfma_f32_16x16x32_bf16 v[96:99], v[196:199], v[212:215], v[96:99]
	v_mfma_f32_16x16x32_bf16 v[84:87], v[188:191], v[220:223], v[84:87]
	v_mfma_f32_16x16x32_bf16 v[80:83], v[196:199], v[220:223], v[80:83]
	v_mfma_f32_16x16x32_bf16 v[68:71], v[188:191], v[228:231], v[68:71]
	v_mfma_f32_16x16x32_bf16 v[64:67], v[196:199], v[228:231], v[64:67]
	s_setprio 0
	s_barrier
	s_add_i32 s79, s74, s38
	v_lshl_add_u64 v[148:149], s[28:29], 0, v[130:131]
	s_mov_b32 m0, s79
	ds_read_b128 v[200:203], v164 offset:16384
	ds_read_b128 v[204:207], v164 offset:17408
	ds_read_b128 v[208:211], v164 offset:18432
	ds_read_b128 v[212:215], v164 offset:19456
	ds_read_b128 v[216:219], v164 offset:20480
	ds_read_b128 v[220:223], v164 offset:21504
	ds_read_b128 v[224:227], v164 offset:22528
	ds_read_b128 v[228:231], v164 offset:23552
	global_load_lds_dwordx4 v[148:149], off
	s_add_i32 m0, s79, 0x2000
	s_add_u32 s80, s28, 0x40000
	v_lshl_add_u64 v[234:235], s[28:29], 0, v[134:135]
	s_addc_u32 s81, s29, 0
	s_add_i32 s79, s75, s38
	global_load_lds_dwordx4 v[234:235], off
	v_lshl_add_u64 v[236:237], s[80:81], 0, v[130:131]
	s_mov_b32 m0, s79
	v_lshl_add_u64 v[238:239], s[30:31], 0, v[132:133]
	global_load_lds_dwordx4 v[236:237], off
	v_lshl_add_u64 v[236:237], s[80:81], 0, v[134:135]
	s_add_i32 m0, s79, 0x2000
	s_nop 0
	global_load_lds_dwordx4 v[236:237], off
	v_lshl_add_u64 v[236:237], s[30:31], 0, v[128:129]
	s_mov_b32 m0, s39
	s_nop 0
	global_load_lds_dwordx4 v[236:237], off
	s_mov_b32 m0, s42
	s_nop 0
	global_load_lds_dwordx4 v[238:239], off
	s_waitcnt vmcnt(8)
	global_load_dword v244, v[254:255], off
	global_load_dword v245, v[254:255], off offset:64
	global_load_dword v246, v[254:255], off offset:128
	global_load_dword v247, v[254:255], off offset:192
	global_load_dword v248, v[254:255], off offset:512
	global_load_dword v249, v[254:255], off offset:576
	global_load_dword v250, v[254:255], off offset:640
	global_load_dword v251, v[254:255], off offset:704
	s_waitcnt lgkmcnt(0)
	s_barrier
	s_setprio 1
	s_waitcnt lgkmcnt(0)
	v_mfma_f32_16x16x32_bf16 v[60:63], v[144:147], v[200:203], v[60:63]
	v_mfma_f32_16x16x32_bf16 v[56:59], v[172:175], v[200:203], v[56:59]
	v_mfma_f32_16x16x32_bf16 v[44:47], v[144:147], v[208:211], v[44:47]
	v_mfma_f32_16x16x32_bf16 v[40:43], v[172:175], v[208:211], v[40:43]
	v_mfma_f32_16x16x32_bf16 v[28:31], v[144:147], v[216:219], v[28:31]
	v_mfma_f32_16x16x32_bf16 v[24:27], v[172:175], v[216:219], v[24:27]
	v_mfma_f32_16x16x32_bf16 v[12:15], v[144:147], v[224:227], v[12:15]
	v_mfma_f32_16x16x32_bf16 v[8:11], v[172:175], v[224:227], v[8:11]
	v_mfma_f32_16x16x32_bf16 v[60:63], v[168:171], v[204:207], v[60:63]
	v_mfma_f32_16x16x32_bf16 v[56:59], v[176:179], v[204:207], v[56:59]
	v_mfma_f32_16x16x32_bf16 v[44:47], v[168:171], v[212:215], v[44:47]
	v_mfma_f32_16x16x32_bf16 v[40:43], v[176:179], v[212:215], v[40:43]
	v_mfma_f32_16x16x32_bf16 v[28:31], v[168:171], v[220:223], v[28:31]
	v_mfma_f32_16x16x32_bf16 v[24:27], v[176:179], v[220:223], v[24:27]
	v_mfma_f32_16x16x32_bf16 v[12:15], v[168:171], v[228:231], v[12:15]
	v_mfma_f32_16x16x32_bf16 v[8:11], v[176:179], v[228:231], v[8:11]
	s_setprio 0
	s_setprio 1
	v_mfma_f32_16x16x32_bf16 v[52:55], v[180:183], v[200:203], v[52:55]
	v_mfma_f32_16x16x32_bf16 v[48:51], v[192:195], v[200:203], v[48:51]
	v_mfma_f32_16x16x32_bf16 v[36:39], v[180:183], v[208:211], v[36:39]
	v_mfma_f32_16x16x32_bf16 v[32:35], v[192:195], v[208:211], v[32:35]
	v_mfma_f32_16x16x32_bf16 v[20:23], v[180:183], v[216:219], v[20:23]
	v_mfma_f32_16x16x32_bf16 v[16:19], v[192:195], v[216:219], v[16:19]
	v_mfma_f32_16x16x32_bf16 v[4:7], v[180:183], v[224:227], v[4:7]
	v_mfma_f32_16x16x32_bf16 v[0:3], v[192:195], v[224:227], v[0:3]
	v_mfma_f32_16x16x32_bf16 v[52:55], v[188:191], v[204:207], v[52:55]
	v_mfma_f32_16x16x32_bf16 v[48:51], v[196:199], v[204:207], v[48:51]
	v_mfma_f32_16x16x32_bf16 v[36:39], v[188:191], v[212:215], v[36:39]
	v_mfma_f32_16x16x32_bf16 v[32:35], v[196:199], v[212:215], v[32:35]
	v_mfma_f32_16x16x32_bf16 v[20:23], v[188:191], v[220:223], v[20:23]
	v_mfma_f32_16x16x32_bf16 v[16:19], v[196:199], v[220:223], v[16:19]
	v_mfma_f32_16x16x32_bf16 v[4:7], v[188:191], v[228:231], v[4:7]
	v_mfma_f32_16x16x32_bf16 v[0:3], v[196:199], v[228:231], v[0:3]
	s_setprio 0
	s_barrier
; #define PG8_STAGE(bufoff, gbase, voff) do { _Pragma("unroll") for (int _i = 0; _i < 2; ++_i) \
;         __builtin_amdgcn_global_load_lds((const unsigned*)((const char*)(gbase) + (voff)[_i]), (PG8_LAS unsigned*)(lds + (bufoff) + ldsw + _i * 8192), 16, 0, 0); } while (0)
; #define PG8_LDA(dst, b, h) do { _Pragma("unroll") for (int m = 0; m < 4; ++m) _Pragma("unroll") for (int k = 0; k < 2; ++k) dst[m][k] = *(const PG8_LAS bf16x8*)(lds + PG8_SA(b, h) + aoff + m * 2048 + k * 1024); } while (0)
; #define PG8_LDB(dst, b, h) do { _Pragma("unroll") for (int n = 0; n < 2; ++n) _Pragma("unroll") for (int k = 0; k < 2; ++k) dst[n][k] = *(const PG8_LAS bf16x8*)(lds + PG8_SB(b, h) + boff + n * 2048 + k * 1024); } while (0)
; #define PG8_MMA(ai, bj, At, Bt) do { __builtin_amdgcn_s_setprio(1); _Pragma("unroll") for (int m = 0; m < 4; ++m) _Pragma("unroll") for (int n = 0; n < 2; ++n) _Pragma("unroll") for (int k = 0; k < 2; ++k) \
;         acc[ai][bj][m][n] = __builtin_amdgcn_mfma_f32_16x16x32_bf16(Bt[n][k], At[m][k], acc[ai][bj][m][n], 0, 0, 0); __builtin_amdgcn_s_setprio(0); } while (0)
; #define PG8_WAIT_V(n) asm volatile("s_waitcnt vmcnt(" #n ")" ::: "memory")
; #define PG8_WAIT_L(n) asm volatile("s_waitcnt lgkmcnt(" #n ")" ::: "memory")
; #define PG8_BAR __builtin_amdgcn_s_barrier()
; #define PG8_SCHED __builtin_amdgcn_sched_barrier(0)
; template <class Epi, class Sched, bool ALIGN_EPI = false, bool SP2 = false>
; __device__ __forceinline__ void gemm_phase(PG8_LAS unsigned char* lds, const Gemm g, const Sched& S, const Epi& E) {
;     ...
;             PG8_LDB(B0, 1, 0); PG8_LDB(B1, 1, 1); PG8_SCHED; PG8_LDA(At, 1, 0); PG8_STAGE(PG8_SA(0, 1), a2 + hstep, voffA);
;             PG8_WAIT_V(8); PG8_WAIT_L(0); PG8_BAR; PG8_MMA(0, 0, At, B0); PG8_MMA(0, 1, At, B1); PG8_BAR; PG8_SCHED;
;             PG8_LDA(At, 1, 1); PG8_STAGE(PG8_SB(1, 0), b3, voffB); PG8_STAGE(PG8_SB(1, 1), b3 + hstep, voffB); PG8_STAGE(PG8_SA(1, 0), a3, voffA);
;             PG8_WAIT_V(8); PG8_WAIT_L(0); PG8_BAR; PG8_MMA(1, 0, At, B0); PG8_MMA(1, 1, At, B1); PG8_BAR; PG8_SCHED;
	s_add_i32 s79, 0, 0x18000
	v_add_u32_e32 v167, s79, v157
	s_add_i32 s80, 0, 0x1c000
	ds_read_b128 v[144:147], v167
	ds_read_b128 v[168:171], v167 offset:1024
	ds_read_b128 v[172:175], v167 offset:2048
	ds_read_b128 v[176:179], v167 offset:3072
	v_add_u32_e32 v167, s80, v157
	ds_read_b128 v[180:183], v167
	ds_read_b128 v[188:191], v167 offset:1024
	ds_read_b128 v[192:195], v167 offset:2048
	ds_read_b128 v[196:199], v167 offset:3072
	s_add_u32 s30, s30, 0x40000
	s_addc_u32 s31, s31, 0
	s_mov_b32 m0, s43
	v_lshl_add_u64 v[240:241], s[30:31], 0, v[128:129]
	ds_read_b128 v[200:203], v164 offset:32768
	ds_read_b128 v[204:207], v164 offset:33792
	ds_read_b128 v[208:211], v164 offset:34816
	ds_read_b128 v[212:215], v164 offset:35840
	ds_read_b128 v[216:219], v164 offset:36864
	ds_read_b128 v[220:223], v164 offset:37888
	ds_read_b128 v[224:227], v164 offset:38912
	ds_read_b128 v[228:231], v164 offset:39936
	global_load_lds_dwordx4 v[240:241], off
	v_lshl_add_u64 v[240:241], s[30:31], 0, v[132:133]
	s_mov_b32 m0, s44
	s_nop 0
	global_load_lds_dwordx4 v[240:241], off
	s_waitcnt vmcnt(16)
	s_waitcnt lgkmcnt(0)
	s_barrier
	s_setprio 1
	s_waitcnt lgkmcnt(0)
	v_mfma_f32_16x16x32_bf16 v[124:127], v[144:147], v[200:203], v[124:127]
	v_mfma_f32_16x16x32_bf16 v[120:123], v[172:175], v[200:203], v[120:123]
	v_mfma_f32_16x16x32_bf16 v[108:111], v[144:147], v[208:211], v[108:111]
	v_mfma_f32_16x16x32_bf16 v[104:107], v[172:175], v[208:211], v[104:107]
	v_mfma_f32_16x16x32_bf16 v[92:95], v[144:147], v[216:219], v[92:95]
	v_mfma_f32_16x16x32_bf16 v[88:91], v[172:175], v[216:219], v[88:91]
	v_mfma_f32_16x16x32_bf16 v[76:79], v[144:147], v[224:227], v[76:79]
	v_mfma_f32_16x16x32_bf16 v[72:75], v[172:175], v[224:227], v[72:75]
	v_mfma_f32_16x16x32_bf16 v[124:127], v[168:171], v[204:207], v[124:127]
	v_mfma_f32_16x16x32_bf16 v[120:123], v[176:179], v[204:207], v[120:123]
	v_mfma_f32_16x16x32_bf16 v[108:111], v[168:171], v[212:215], v[108:111]
	v_mfma_f32_16x16x32_bf16 v[104:107], v[176:179], v[212:215], v[104:107]
	v_mfma_f32_16x16x32_bf16 v[92:95], v[168:171], v[220:223], v[92:95]
	v_mfma_f32_16x16x32_bf16 v[88:91], v[176:179], v[220:223], v[88:91]
	v_mfma_f32_16x16x32_bf16 v[76:79], v[168:171], v[228:231], v[76:79]
	v_mfma_f32_16x16x32_bf16 v[72:75], v[176:179], v[228:231], v[72:75]
	s_setprio 0
	s_setprio 1
	v_mfma_f32_16x16x32_bf16 v[116:119], v[180:183], v[200:203], v[116:119]
	v_mfma_f32_16x16x32_bf16 v[112:115], v[192:195], v[200:203], v[112:115]
	v_mfma_f32_16x16x32_bf16 v[100:103], v[180:183], v[208:211], v[100:103]
	v_mfma_f32_16x16x32_bf16 v[96:99], v[192:195], v[208:211], v[96:99]
	v_mfma_f32_16x16x32_bf16 v[84:87], v[180:183], v[216:219], v[84:87]
	v_mfma_f32_16x16x32_bf16 v[80:83], v[192:195], v[216:219], v[80:83]
	v_mfma_f32_16x16x32_bf16 v[68:71], v[180:183], v[224:227], v[68:71]
	v_mfma_f32_16x16x32_bf16 v[64:67], v[192:195], v[224:227], v[64:67]
	v_mfma_f32_16x16x32_bf16 v[116:119], v[188:191], v[204:207], v[116:119]
	v_mfma_f32_16x16x32_bf16 v[112:115], v[196:199], v[204:207], v[112:115]
	v_mfma_f32_16x16x32_bf16 v[100:103], v[188:191], v[212:215], v[100:103]
	v_mfma_f32_16x16x32_bf16 v[96:99], v[196:199], v[212:215], v[96:99]
	v_mfma_f32_16x16x32_bf16 v[84:87], v[188:191], v[220:223], v[84:87]
	v_mfma_f32_16x16x32_bf16 v[80:83], v[196:199], v[220:223], v[80:83]
	v_mfma_f32_16x16x32_bf16 v[68:71], v[188:191], v[228:231], v[68:71]
	v_mfma_f32_16x16x32_bf16 v[64:67], v[196:199], v[228:231], v[64:67]
	s_setprio 0
	s_barrier
	s_add_i32 s30, s79, s38
	v_lshl_add_u64 v[148:149], v[148:149], 0, s[12:13]
	s_mov_b32 m0, s30
	ds_read_b128 v[200:203], v164 offset:49152
	ds_read_b128 v[204:207], v164 offset:50176
	ds_read_b128 v[208:211], v164 offset:51200
	ds_read_b128 v[212:215], v164 offset:52224
	ds_read_b128 v[216:219], v164 offset:53248
	ds_read_b128 v[220:223], v164 offset:54272
	ds_read_b128 v[224:227], v164 offset:55296
	ds_read_b128 v[228:231], v164 offset:56320
	global_load_lds_dwordx4 v[148:149], off
	s_add_i32 m0, s30, 0x2000
	s_add_u32 s28, s28, 0x40080
	v_lshl_add_u64 v[148:149], v[234:235], 0, s[12:13]
	s_addc_u32 s29, s29, 0
	s_add_i32 s30, s80, s38
	global_load_lds_dwordx4 v[148:149], off
	v_lshl_add_u64 v[148:149], s[28:29], 0, v[130:131]
	s_mov_b32 m0, s30
	s_nop 0
	global_load_lds_dwordx4 v[148:149], off
	v_lshl_add_u64 v[148:149], s[28:29], 0, v[134:135]
	s_add_i32 m0, s30, 0x2000
	s_nop 0
	global_load_lds_dwordx4 v[148:149], off
	v_lshl_add_u64 v[148:149], v[236:237], 0, s[12:13]
	s_mov_b32 m0, s50
	s_nop 0
	global_load_lds_dwordx4 v[148:149], off
	v_lshl_add_u64 v[148:149], v[238:239], 0, s[12:13]
	s_mov_b32 m0, s51
	s_nop 0
	global_load_lds_dwordx4 v[148:149], off
	s_waitcnt vmcnt(8)
	s_waitcnt lgkmcnt(0)
	s_barrier
; __device__ __forceinline__ unsigned cvt_pk_bf16(float lo, float hi) { unsigned r; asm volatile("v_cvt_pk_bf16_f32 %0, %1, %2" : "=v"(r) : "v"(lo), "v"(hi)); return r; }
; #define PG8_MMA(ai, bj, At, Bt) do { __builtin_amdgcn_s_setprio(1); _Pragma("unroll") for (int m = 0; m < 4; ++m) _Pragma("unroll") for (int n = 0; n < 2; ++n) _Pragma("unroll") for (int k = 0; k < 2; ++k) \
;         acc[ai][bj][m][n] = __builtin_amdgcn_mfma_f32_16x16x32_bf16(Bt[n][k], At[m][k], acc[ai][bj][m][n], 0, 0, 0); __builtin_amdgcn_s_setprio(0); } while (0)
; #define PG8_WAIT_V(n) asm volatile("s_waitcnt vmcnt(" #n ")" ::: "memory")
; #define PG8_WAIT_L(n) asm volatile("s_waitcnt lgkmcnt(" #n ")" ::: "memory")
; #define PG8_BAR __builtin_amdgcn_s_barrier()
;     __device__ __forceinline__ void operator()(const f32x4 (&acc)[2][2][4][2], const Unit& u, int wr, int wc, int fr, int fq) const {
;         const int row0 = u.pm * BM + wr * 64 + fr, colt = u.pn * BM, region = colt >> 10;
;         const float sc = (region == 0) ? qscale : 1.f;
;         bf16_t* base = QF + (size_t)region * ((size_t)16384 * 1024);
; #pragma unroll
;         for (int ai = 0; ai < 2; ++ai)
; #pragma unroll
;             for (int m = 0; m < 4; ++m) { const int row = row0 + ai * HALF + m * 16;
;                 const float rs = __builtin_amdgcn_rsqf(ssq[row] * (1.0f / 1024.0f) + 1e-6f) * sc;
;                 const int b = row >> 12, tl = row & 4095, tile = tl >> 5, r = tl & 31;
; #pragma unroll
;                 for (int bj = 0; bj < 2; ++bj) { const int cc = (colt & 1023) + bj * HALF + wc * 32 + 8 * fq, h = cc >> 6, d8 = cc & 63, bh = b * 16 + h;
;                     const f32x4 v0 = acc[ai][bj][m][0] * rs, v1 = acc[ai][bj][m][1] * rs;
;                     u32x4 w; w.x = cvt_pk_bf16(v0[0], v0[1]); w.y = cvt_pk_bf16(v0[2], v0[3]); w.z = cvt_pk_bf16(v1[0], v1[1]); w.w = cvt_pk_bf16(v1[2], v1[3]);
;                     if (region < 2) { const int ks = d8 >> 4, hh = (d8 >> 3) & 1;
;                         *(u32x4*)(base + ((size_t)(((bh * 128 + tile) * 4 + ks) * 64 + hh * 32 + r) << 3)) = w;
; template <class Epi, class Sched, bool ALIGN_EPI = false, bool SP2 = false>
; __device__ __forceinline__ void gemm_phase(PG8_LAS unsigned char* lds, const Gemm g, const Sched& S, const Epi& E) {
;     ...
;             PG8_WAIT_V(8); PG8_WAIT_L(0); PG8_BAR; PG8_MMA(1, 0, At, B0); PG8_MMA(1, 1, At, B1); PG8_BAR; PG8_SCHED;
	s_setprio 1
	s_waitcnt lgkmcnt(0)
	v_mfma_f32_16x16x32_bf16 v[60:63], v[144:147], v[200:203], v[60:63]
	v_mfma_f32_16x16x32_bf16 v[56:59], v[172:175], v[200:203], v[56:59]
	v_mfma_f32_16x16x32_bf16 v[44:47], v[144:147], v[208:211], v[44:47]
	v_mfma_f32_16x16x32_bf16 v[40:43], v[172:175], v[208:211], v[40:43]
	v_mfma_f32_16x16x32_bf16 v[28:31], v[144:147], v[216:219], v[28:31]
	v_mfma_f32_16x16x32_bf16 v[24:27], v[172:175], v[216:219], v[24:27]
	v_mfma_f32_16x16x32_bf16 v[12:15], v[144:147], v[224:227], v[12:15]
	v_mfma_f32_16x16x32_bf16 v[8:11], v[172:175], v[224:227], v[8:11]
	v_mfma_f32_16x16x32_bf16 v[60:63], v[168:171], v[204:207], v[60:63]
	v_mfma_f32_16x16x32_bf16 v[56:59], v[176:179], v[204:207], v[56:59]
	v_mfma_f32_16x16x32_bf16 v[44:47], v[168:171], v[212:215], v[44:47]
	v_mfma_f32_16x16x32_bf16 v[40:43], v[176:179], v[212:215], v[40:43]
	v_mfma_f32_16x16x32_bf16 v[28:31], v[168:171], v[220:223], v[28:31]
	v_mfma_f32_16x16x32_bf16 v[24:27], v[176:179], v[220:223], v[24:27]
	v_mfma_f32_16x16x32_bf16 v[12:15], v[168:171], v[228:231], v[12:15]
	v_mfma_f32_16x16x32_bf16 v[8:11], v[176:179], v[228:231], v[8:11]
	s_setprio 0
	s_setprio 1
	v_mfma_f32_16x16x32_bf16 v[52:55], v[180:183], v[200:203], v[52:55]
	v_mfma_f32_16x16x32_bf16 v[48:51], v[192:195], v[200:203], v[48:51]
	v_mfma_f32_16x16x32_bf16 v[36:39], v[180:183], v[208:211], v[36:39]
	v_mfma_f32_16x16x32_bf16 v[32:35], v[192:195], v[208:211], v[32:35]
	v_mfma_f32_16x16x32_bf16 v[20:23], v[180:183], v[216:219], v[20:23]
	v_mfma_f32_16x16x32_bf16 v[16:19], v[192:195], v[216:219], v[16:19]
	v_mfma_f32_16x16x32_bf16 v[4:7], v[180:183], v[224:227], v[4:7]
	v_mfma_f32_16x16x32_bf16 v[0:3], v[192:195], v[224:227], v[0:3]
	v_mfma_f32_16x16x32_bf16 v[52:55], v[188:191], v[204:207], v[52:55]
	v_mfma_f32_16x16x32_bf16 v[48:51], v[196:199], v[204:207], v[48:51]
	v_mfma_f32_16x16x32_bf16 v[36:39], v[188:191], v[212:215], v[36:39]
	v_mfma_f32_16x16x32_bf16 v[32:35], v[196:199], v[212:215], v[32:35]
	v_mfma_f32_16x16x32_bf16 v[20:23], v[188:191], v[220:223], v[20:23]
	v_mfma_f32_16x16x32_bf16 v[16:19], v[196:199], v[220:223], v[16:19]
	v_mfma_f32_16x16x32_bf16 v[4:7], v[188:191], v[228:231], v[4:7]
	v_mfma_f32_16x16x32_bf16 v[0:3], v[196:199], v[228:231], v[0:3]
	s_setprio 0
	s_barrier
	s_add_i32 s78, s78, 2
	s_add_u32 s26, s26, 0x100
	s_addc_u32 s27, s27, 0
	s_add_u32 s76, s76, 0x100
	s_addc_u32 s77, s77, 0
	s_cmp_gt_u32 s78, 13
	s_cbranch_scc0 .LBB0_490
	s_and_b64 vcc, exec, s[14:15]
	s_cbranch_vccz .LBB0_493
	s_barrier
.LBB0_493:
	s_lshl_b32 s5, s24, 8
	s_add_i32 s17, s5, s48
	v_or_b32_e32 v144, s17, v162
	v_ashrrev_i32_e32 v145, 31, v144
	v_lshl_add_u64 v[146:147], v[144:145], 2, s[8:9]
	s_nop 0
	s_lshl_b32 s19, s4, 8
	s_ashr_i32 s26, s4, 2
	s_cmp_lt_u32 s4, 4
	s_cselect_b64 vcc, -1, 0
	s_ashr_i32 s27, s26, 31
	s_lshl_b64 s[4:5], s[26:27], 25
	s_add_u32 s24, s46, s4
	s_addc_u32 s25, s47, s5
	s_and_b32 s4, s19, 0x300
	s_or_b32 s4, s4, s49
	s_cmp_gt_i32 s26, 1
	s_cselect_b64 s[26:27], -1, 0
	s_lshr_b32 s19, s17, 5
	v_cndmask_b32_e32 v145, 1.0, v166, vcc
	s_ashr_i32 s5, s17, 8
	s_and_b32 s31, s19, 0x7e
	s_lshr_b32 s17, s4, 6
	s_and_b32 s4, s5, -16
	s_lshl_b32 s5, s31, 3
	s_mov_b64 s[28:29], -1
	s_and_b64 vcc, exec, s[26:27]
	s_or_b32 s30, s4, s17
	s_or_b32 s76, s5, s69
	s_waitcnt vmcnt(8)
	v_fmamk_f32 v148, v244, 0x3a800000, v165
	v_rsq_f32_e32 v148, v148
	s_nop 0
	v_mul_f32_e32 v148, v145, v148
	v_pk_mul_f32 v[168:169], v[122:123], v[148:149] op_sel_hi:[1,0]
	v_pk_mul_f32 v[122:123], v[120:121], v[148:149] op_sel_hi:[1,0]
	v_pk_mul_f32 v[126:127], v[126:127], v[148:149] op_sel_hi:[1,0]
	v_pk_mul_f32 v[124:125], v[124:125], v[148:149] op_sel_hi:[1,0]
	s_nop 0
	v_cvt_pk_bf16_f32 v120, v124, v125
	v_cvt_pk_bf16_f32 v121, v126, v127
	v_cvt_pk_bf16_f32 v122, v122, v123
	v_cvt_pk_bf16_f32 v123, v168, v169
	s_cbranch_vccz .LBB0_495
	s_lshl_b32 s5, s30, 10
	s_or_b32 s5, s76, s5
	v_or_b32_e32 v124, s5, v154
	v_lshl_or_b32 v124, v124, 6, v162
	v_ashrrev_i32_e32 v125, 31, v124
	v_lshl_add_u64 v[124:125], v[124:125], 3, s[24:25]
	global_store_dwordx2 v[124:125], v[120:121], off
	global_store_dwordx2 v[124:125], v[122:123], off offset:256
	s_mov_b64 s[28:29], 0

; __device__ __forceinline__ unsigned cvt_pk_bf16(float lo, float hi) { unsigned r; asm volatile("v_cvt_pk_bf16_f32 %0, %1, %2" : "=v"(r) : "v"(lo), "v"(hi)); return r; }
;     __device__ __forceinline__ void operator()(const f32x4 (&acc)[2][2][4][2], const Unit& u, int wr, int wc, int fr, int fq) const {
;     ...
;             for (int m = 0; m < 4; ++m) { const int row = row0 + ai * HALF + m * 16;
;                 const float rs = __builtin_amdgcn_rsqf(ssq[row] * (1.0f / 1024.0f) + 1e-6f) * sc;
;                 const int b = row >> 12, tl = row & 4095, tile = tl >> 5, r = tl & 31;
; #pragma unroll
;                 for (int bj = 0; bj < 2; ++bj) { const int cc = (colt & 1023) + bj * HALF + wc * 32 + 8 * fq, h = cc >> 6, d8 = cc & 63, bh = b * 16 + h;
;                     const f32x4 v0 = acc[ai][bj][m][0] * rs, v1 = acc[ai][bj][m][1] * rs;
;                     u32x4 w; w.x = cvt_pk_bf16(v0[0], v0[1]); w.y = cvt_pk_bf16(v0[2], v0[3]); w.z = cvt_pk_bf16(v1[0], v1[1]); w.w = cvt_pk_bf16(v1[2], v1[3]);
;                     if (region < 2) { const int ks = d8 >> 4, hh = (d8 >> 3) & 1;
;                         *(u32x4*)(base + ((size_t)(((bh * 128 + tile) * 4 + ks) * 64 + hh * 32 + r) << 3)) = w;
;                     } else { const int dt = d8 >> 5, g = (d8 >> 3) & 3; bf16_t* p = base + ((size_t)((((bh * 128 + tile) * 2 + dt) * 4 + g) * 64 + r) << 2);
;                         *(unsigned long long*)p = (unsigned long long)w.x | ((unsigned long long)w.y << 32);
;                         *(unsigned long long*)(p + 128) = (unsigned long long)w.z | ((unsigned long long)w.w << 32); } }
.LBB0_501:
	s_nop 0
	s_and_b64 vcc, exec, s[4:5]
	s_mov_b64 s[26:27], -1
	s_nop 0
	v_fmamk_f32 v112, v245, 0x3a800000, v165
	v_rsq_f32_e32 v112, v112
	s_nop 0
	v_mul_f32_e32 v112, v145, v112
	v_pk_mul_f32 v[114:115], v[106:107], v[112:113] op_sel_hi:[1,0]
	v_pk_mul_f32 v[106:107], v[104:105], v[112:113] op_sel_hi:[1,0]
	v_pk_mul_f32 v[110:111], v[110:111], v[112:113] op_sel_hi:[1,0]
	v_pk_mul_f32 v[108:109], v[108:109], v[112:113] op_sel_hi:[1,0]
	s_nop 0
	v_cvt_pk_bf16_f32 v104, v108, v109
	v_cvt_pk_bf16_f32 v105, v110, v111
	v_cvt_pk_bf16_f32 v106, v106, v107
	v_cvt_pk_bf16_f32 v107, v114, v115
	s_cbranch_vccnz .LBB0_503
	s_lshl_b32 s26, s30, 10
	s_or_b32 s26, s76, s26
	v_or_b32_e32 v108, s26, v154
	v_lshl_or_b32 v108, v108, 6, v158
	v_ashrrev_i32_e32 v109, 31, v108
	v_lshl_add_u64 v[108:109], v[108:109], 3, s[24:25]
	s_mov_b64 s[26:27], 0
	global_store_dwordx2 v[108:109], v[104:105], off
	global_store_dwordx2 v[108:109], v[106:107], off offset:256

; __device__ __forceinline__ unsigned cvt_pk_bf16(float lo, float hi) { unsigned r; asm volatile("v_cvt_pk_bf16_f32 %0, %1, %2" : "=v"(r) : "v"(lo), "v"(hi)); return r; }
;     __device__ __forceinline__ void operator()(const f32x4 (&acc)[2][2][4][2], const Unit& u, int wr, int wc, int fr, int fq) const {
;     ...
;             for (int m = 0; m < 4; ++m) { const int row = row0 + ai * HALF + m * 16;
;                 const float rs = __builtin_amdgcn_rsqf(ssq[row] * (1.0f / 1024.0f) + 1e-6f) * sc;
;                 const int b = row >> 12, tl = row & 4095, tile = tl >> 5, r = tl & 31;
; #pragma unroll
;                 for (int bj = 0; bj < 2; ++bj) { const int cc = (colt & 1023) + bj * HALF + wc * 32 + 8 * fq, h = cc >> 6, d8 = cc & 63, bh = b * 16 + h;
;                     const f32x4 v0 = acc[ai][bj][m][0] * rs, v1 = acc[ai][bj][m][1] * rs;
;                     u32x4 w; w.x = cvt_pk_bf16(v0[0], v0[1]); w.y = cvt_pk_bf16(v0[2], v0[3]); w.z = cvt_pk_bf16(v1[0], v1[1]); w.w = cvt_pk_bf16(v1[2], v1[3]);
;                     if (region < 2) { const int ks = d8 >> 4, hh = (d8 >> 3) & 1;
;                         *(u32x4*)(base + ((size_t)(((bh * 128 + tile) * 4 + ks) * 64 + hh * 32 + r) << 3)) = w;
;                     } else { const int dt = d8 >> 5, g = (d8 >> 3) & 3; bf16_t* p = base + ((size_t)((((bh * 128 + tile) * 2 + dt) * 4 + g) * 64 + r) << 2);
;                         *(unsigned long long*)p = (unsigned long long)w.x | ((unsigned long long)w.y << 32);
;                         *(unsigned long long*)(p + 128) = (unsigned long long)w.z | ((unsigned long long)w.w << 32); } }
.LBB0_509:
	s_nop 1
	v_or_b32_e32 v96, 32, v144
	v_ashrrev_i32_e32 v97, 31, v96
	v_lshl_add_u64 v[98:99], v[96:97], 2, s[8:9]
	s_nop 0
	s_and_b64 vcc, exec, s[4:5]
	s_mov_b64 s[26:27], -1
	s_nop 0
	v_fmamk_f32 v97, v246, 0x3a800000, v165
	v_rsq_f32_e32 v99, v97
	v_bfe_u32 v97, v96, 5, 7
	v_lshl_or_b32 v98, v97, 3, s58
	v_mul_f32_e32 v96, v145, v99
	v_pk_mul_f32 v[100:101], v[90:91], v[96:97] op_sel_hi:[1,0]
	v_pk_mul_f32 v[90:91], v[88:89], v[96:97] op_sel_hi:[1,0]
	v_pk_mul_f32 v[94:95], v[94:95], v[96:97] op_sel_hi:[1,0]
	v_pk_mul_f32 v[92:93], v[92:93], v[96:97] op_sel_hi:[1,0]
	s_nop 0
	v_cvt_pk_bf16_f32 v88, v92, v93
	v_cvt_pk_bf16_f32 v89, v94, v95
	v_cvt_pk_bf16_f32 v90, v90, v91
	v_cvt_pk_bf16_f32 v91, v100, v101
	s_cbranch_vccnz .LBB0_511
	s_lshl_b32 s26, s30, 10
	v_or3_b32 v92, v98, s26, v154
	v_lshl_or_b32 v92, v92, 6, v162
	v_ashrrev_i32_e32 v93, 31, v92
	v_lshl_add_u64 v[92:93], v[92:93], 3, s[24:25]
	s_mov_b64 s[26:27], 0
	global_store_dwordx2 v[92:93], v[88:89], off
	global_store_dwordx2 v[92:93], v[90:91], off offset:256

; __device__ __forceinline__ unsigned cvt_pk_bf16(float lo, float hi) { unsigned r; asm volatile("v_cvt_pk_bf16_f32 %0, %1, %2" : "=v"(r) : "v"(lo), "v"(hi)); return r; }
;     __device__ __forceinline__ void operator()(const f32x4 (&acc)[2][2][4][2], const Unit& u, int wr, int wc, int fr, int fq) const {
;     ...
;             for (int m = 0; m < 4; ++m) { const int row = row0 + ai * HALF + m * 16;
;                 const float rs = __builtin_amdgcn_rsqf(ssq[row] * (1.0f / 1024.0f) + 1e-6f) * sc;
;                 const int b = row >> 12, tl = row & 4095, tile = tl >> 5, r = tl & 31;
; #pragma unroll
;                 for (int bj = 0; bj < 2; ++bj) { const int cc = (colt & 1023) + bj * HALF + wc * 32 + 8 * fq, h = cc >> 6, d8 = cc & 63, bh = b * 16 + h;
;                     const f32x4 v0 = acc[ai][bj][m][0] * rs, v1 = acc[ai][bj][m][1] * rs;
;                     u32x4 w; w.x = cvt_pk_bf16(v0[0], v0[1]); w.y = cvt_pk_bf16(v0[2], v0[3]); w.z = cvt_pk_bf16(v1[0], v1[1]); w.w = cvt_pk_bf16(v1[2], v1[3]);
;                     if (region < 2) { const int ks = d8 >> 4, hh = (d8 >> 3) & 1;
;                         *(u32x4*)(base + ((size_t)(((bh * 128 + tile) * 4 + ks) * 64 + hh * 32 + r) << 3)) = w;
;                     } else { const int dt = d8 >> 5, g = (d8 >> 3) & 3; bf16_t* p = base + ((size_t)((((bh * 128 + tile) * 2 + dt) * 4 + g) * 64 + r) << 2);
;                         *(unsigned long long*)p = (unsigned long long)w.x | ((unsigned long long)w.y << 32);
;                         *(unsigned long long*)(p + 128) = (unsigned long long)w.z | ((unsigned long long)w.w << 32); } }
.LBB0_517:
	s_nop 1
	v_or_b32_e32 v80, 48, v144
	v_ashrrev_i32_e32 v81, 31, v80
	v_lshl_add_u64 v[82:83], v[80:81], 2, s[8:9]
	s_nop 0
	s_and_b64 vcc, exec, s[4:5]
	s_mov_b64 s[26:27], -1
	s_nop 0
	v_fmamk_f32 v81, v247, 0x3a800000, v165
	v_rsq_f32_e32 v83, v81
	v_bfe_u32 v81, v80, 5, 7
	v_lshl_or_b32 v82, v81, 3, s58
	v_mul_f32_e32 v80, v145, v83
	v_pk_mul_f32 v[84:85], v[74:75], v[80:81] op_sel_hi:[1,0]
	v_pk_mul_f32 v[74:75], v[72:73], v[80:81] op_sel_hi:[1,0]
	v_pk_mul_f32 v[78:79], v[78:79], v[80:81] op_sel_hi:[1,0]
	v_pk_mul_f32 v[76:77], v[76:77], v[80:81] op_sel_hi:[1,0]
	s_nop 0
	v_cvt_pk_bf16_f32 v72, v76, v77
	v_cvt_pk_bf16_f32 v73, v78, v79
	v_cvt_pk_bf16_f32 v74, v74, v75
	v_cvt_pk_bf16_f32 v75, v84, v85
	s_cbranch_vccnz .LBB0_519
	s_lshl_b32 s26, s30, 10
	v_or3_b32 v76, v82, s26, v154
	v_lshl_or_b32 v76, v76, 6, v158
	v_ashrrev_i32_e32 v77, 31, v76
	v_lshl_add_u64 v[76:77], v[76:77], 3, s[24:25]
	s_mov_b64 s[26:27], 0
	global_store_dwordx2 v[76:77], v[72:73], off
	global_store_dwordx2 v[76:77], v[74:75], off offset:256

; __device__ __forceinline__ unsigned cvt_pk_bf16(float lo, float hi) { unsigned r; asm volatile("v_cvt_pk_bf16_f32 %0, %1, %2" : "=v"(r) : "v"(lo), "v"(hi)); return r; }
;     __device__ __forceinline__ void operator()(const f32x4 (&acc)[2][2][4][2], const Unit& u, int wr, int wc, int fr, int fq) const {
;     ...
;             for (int m = 0; m < 4; ++m) { const int row = row0 + ai * HALF + m * 16;
;                 const float rs = __builtin_amdgcn_rsqf(ssq[row] * (1.0f / 1024.0f) + 1e-6f) * sc;
;                 const int b = row >> 12, tl = row & 4095, tile = tl >> 5, r = tl & 31;
; #pragma unroll
;                 for (int bj = 0; bj < 2; ++bj) { const int cc = (colt & 1023) + bj * HALF + wc * 32 + 8 * fq, h = cc >> 6, d8 = cc & 63, bh = b * 16 + h;
;                     const f32x4 v0 = acc[ai][bj][m][0] * rs, v1 = acc[ai][bj][m][1] * rs;
;                     u32x4 w; w.x = cvt_pk_bf16(v0[0], v0[1]); w.y = cvt_pk_bf16(v0[2], v0[3]); w.z = cvt_pk_bf16(v1[0], v1[1]); w.w = cvt_pk_bf16(v1[2], v1[3]);
;                     if (region < 2) { const int ks = d8 >> 4, hh = (d8 >> 3) & 1;
;                         *(u32x4*)(base + ((size_t)(((bh * 128 + tile) * 4 + ks) * 64 + hh * 32 + r) << 3)) = w;
;                     } else { const int dt = d8 >> 5, g = (d8 >> 3) & 3; bf16_t* p = base + ((size_t)((((bh * 128 + tile) * 2 + dt) * 4 + g) * 64 + r) << 2);
;                         *(unsigned long long*)p = (unsigned long long)w.x | ((unsigned long long)w.y << 32);
;                         *(unsigned long long*)(p + 128) = (unsigned long long)w.z | ((unsigned long long)w.w << 32); } }
.LBB0_525:
	s_nop 0
	s_nop 0
	v_add_u32_e32 v65, 0x80, v144
	v_ashrrev_i32_e32 v66, 8, v65
	v_lshrrev_b32_e32 v65, 5, v65
	v_and_b32_e32 v67, -16, v66
	v_and_b32_e32 v65, 0x7e, v65
	v_or_b32_e32 v68, s17, v67
	s_mov_b64 s[26:27], -1
	s_and_b64 vcc, exec, s[4:5]
	v_lshl_or_b32 v66, v65, 3, s69
	s_nop 0
	v_fmamk_f32 v64, v248, 0x3a800000, v165
	v_rsq_f32_e32 v64, v64
	s_nop 0
	v_mul_f32_e32 v64, v145, v64
	v_pk_mul_f32 v[60:61], v[60:61], v[64:65] op_sel_hi:[1,0]
	v_pk_mul_f32 v[70:71], v[58:59], v[64:65] op_sel_hi:[1,0]
	v_pk_mul_f32 v[58:59], v[56:57], v[64:65] op_sel_hi:[1,0]
	v_cvt_pk_bf16_f32 v56, v60, v61
	v_lshlrev_b32_e32 v61, 10, v68
	v_pk_mul_f32 v[62:63], v[62:63], v[64:65] op_sel_hi:[1,0]
	s_nop 0
	v_cvt_pk_bf16_f32 v57, v62, v63
	v_cvt_pk_bf16_f32 v58, v58, v59
	v_cvt_pk_bf16_f32 v59, v70, v71
	s_cbranch_vccnz .LBB0_527
	v_or3_b32 v60, v66, v61, v154
	v_lshl_or_b32 v62, v60, 6, v162
	v_ashrrev_i32_e32 v63, 31, v62
	v_lshl_add_u64 v[62:63], v[62:63], 3, s[24:25]
	s_mov_b64 s[26:27], 0
	global_store_dwordx2 v[62:63], v[56:57], off
	global_store_dwordx2 v[62:63], v[58:59], off offset:256

; __device__ __forceinline__ unsigned cvt_pk_bf16(float lo, float hi) { unsigned r; asm volatile("v_cvt_pk_bf16_f32 %0, %1, %2" : "=v"(r) : "v"(lo), "v"(hi)); return r; }
;     __device__ __forceinline__ void operator()(const f32x4 (&acc)[2][2][4][2], const Unit& u, int wr, int wc, int fr, int fq) const {
;     ...
;             for (int m = 0; m < 4; ++m) { const int row = row0 + ai * HALF + m * 16;
;                 const float rs = __builtin_amdgcn_rsqf(ssq[row] * (1.0f / 1024.0f) + 1e-6f) * sc;
;                 const int b = row >> 12, tl = row & 4095, tile = tl >> 5, r = tl & 31;
; #pragma unroll
;                 for (int bj = 0; bj < 2; ++bj) { const int cc = (colt & 1023) + bj * HALF + wc * 32 + 8 * fq, h = cc >> 6, d8 = cc & 63, bh = b * 16 + h;
;                     const f32x4 v0 = acc[ai][bj][m][0] * rs, v1 = acc[ai][bj][m][1] * rs;
;                     u32x4 w; w.x = cvt_pk_bf16(v0[0], v0[1]); w.y = cvt_pk_bf16(v0[2], v0[3]); w.z = cvt_pk_bf16(v1[0], v1[1]); w.w = cvt_pk_bf16(v1[2], v1[3]);
;                     if (region < 2) { const int ks = d8 >> 4, hh = (d8 >> 3) & 1;
;                         *(u32x4*)(base + ((size_t)(((bh * 128 + tile) * 4 + ks) * 64 + hh * 32 + r) << 3)) = w;
;                     } else { const int dt = d8 >> 5, g = (d8 >> 3) & 3; bf16_t* p = base + ((size_t)((((bh * 128 + tile) * 2 + dt) * 4 + g) * 64 + r) << 2);
;                         *(unsigned long long*)p = (unsigned long long)w.x | ((unsigned long long)w.y << 32);
;                         *(unsigned long long*)(p + 128) = (unsigned long long)w.z | ((unsigned long long)w.w << 32); } }
.LBB0_533:
	s_nop 0
	s_nop 0
	v_add_u32_e32 v49, 0x90, v144
	v_lshrrev_b32_e32 v49, 5, v49
	v_and_b32_e32 v49, 0x7e, v49
	s_and_b64 vcc, exec, s[4:5]
	v_lshl_or_b32 v50, v49, 3, s69
	s_mov_b64 s[26:27], -1
	s_nop 0
	v_fmamk_f32 v48, v249, 0x3a800000, v165
	v_rsq_f32_e32 v48, v48
	s_nop 0
	v_mul_f32_e32 v48, v145, v48
	v_pk_mul_f32 v[54:55], v[42:43], v[48:49] op_sel_hi:[1,0]
	v_pk_mul_f32 v[42:43], v[40:41], v[48:49] op_sel_hi:[1,0]
	v_pk_mul_f32 v[46:47], v[46:47], v[48:49] op_sel_hi:[1,0]
	v_pk_mul_f32 v[44:45], v[44:45], v[48:49] op_sel_hi:[1,0]
	s_nop 0
	v_cvt_pk_bf16_f32 v40, v44, v45
	v_cvt_pk_bf16_f32 v41, v46, v47
	v_cvt_pk_bf16_f32 v42, v42, v43
	v_cvt_pk_bf16_f32 v43, v54, v55
	s_cbranch_vccnz .LBB0_535
	v_or3_b32 v44, v50, v61, v154
	v_lshl_or_b32 v44, v44, 6, v158
	v_ashrrev_i32_e32 v45, 31, v44
	v_lshl_add_u64 v[44:45], v[44:45], 3, s[24:25]
	s_mov_b64 s[26:27], 0
	global_store_dwordx2 v[44:45], v[40:41], off
	global_store_dwordx2 v[44:45], v[42:43], off offset:256

; __device__ __forceinline__ unsigned cvt_pk_bf16(float lo, float hi) { unsigned r; asm volatile("v_cvt_pk_bf16_f32 %0, %1, %2" : "=v"(r) : "v"(lo), "v"(hi)); return r; }
;     __device__ __forceinline__ void operator()(const f32x4 (&acc)[2][2][4][2], const Unit& u, int wr, int wc, int fr, int fq) const {
;     ...
;             for (int m = 0; m < 4; ++m) { const int row = row0 + ai * HALF + m * 16;
;                 const float rs = __builtin_amdgcn_rsqf(ssq[row] * (1.0f / 1024.0f) + 1e-6f) * sc;
;                 const int b = row >> 12, tl = row & 4095, tile = tl >> 5, r = tl & 31;
; #pragma unroll
;                 for (int bj = 0; bj < 2; ++bj) { const int cc = (colt & 1023) + bj * HALF + wc * 32 + 8 * fq, h = cc >> 6, d8 = cc & 63, bh = b * 16 + h;
;                     const f32x4 v0 = acc[ai][bj][m][0] * rs, v1 = acc[ai][bj][m][1] * rs;
;                     u32x4 w; w.x = cvt_pk_bf16(v0[0], v0[1]); w.y = cvt_pk_bf16(v0[2], v0[3]); w.z = cvt_pk_bf16(v1[0], v1[1]); w.w = cvt_pk_bf16(v1[2], v1[3]);
;                     if (region < 2) { const int ks = d8 >> 4, hh = (d8 >> 3) & 1;
;                         *(u32x4*)(base + ((size_t)(((bh * 128 + tile) * 4 + ks) * 64 + hh * 32 + r) << 3)) = w;
;                     } else { const int dt = d8 >> 5, g = (d8 >> 3) & 3; bf16_t* p = base + ((size_t)((((bh * 128 + tile) * 2 + dt) * 4 + g) * 64 + r) << 2);
;                         *(unsigned long long*)p = (unsigned long long)w.x | ((unsigned long long)w.y << 32);
;                         *(unsigned long long*)(p + 128) = (unsigned long long)w.z | ((unsigned long long)w.w << 32); } }
.LBB0_541:
	s_nop 0
	s_nop 0
	v_add_u32_e32 v33, 0xa0, v144
	v_bfe_u32 v33, v33, 5, 7
	s_and_b64 vcc, exec, s[4:5]
	v_lshl_or_b32 v34, v33, 3, s69
	s_mov_b64 s[26:27], -1
	s_nop 0
	v_fmamk_f32 v32, v250, 0x3a800000, v165
	v_rsq_f32_e32 v32, v32
	s_nop 0
	v_mul_f32_e32 v32, v145, v32
	v_pk_mul_f32 v[36:37], v[26:27], v[32:33] op_sel_hi:[1,0]
	v_pk_mul_f32 v[26:27], v[24:25], v[32:33] op_sel_hi:[1,0]
	v_pk_mul_f32 v[30:31], v[30:31], v[32:33] op_sel_hi:[1,0]
	v_pk_mul_f32 v[28:29], v[28:29], v[32:33] op_sel_hi:[1,0]
	s_nop 0
	v_cvt_pk_bf16_f32 v24, v28, v29
	v_cvt_pk_bf16_f32 v25, v30, v31
	v_cvt_pk_bf16_f32 v26, v26, v27
	v_cvt_pk_bf16_f32 v27, v36, v37
	s_cbranch_vccnz .LBB0_543
	v_or3_b32 v28, v34, v61, v154
	v_lshl_or_b32 v28, v28, 6, v162
	v_ashrrev_i32_e32 v29, 31, v28
	v_lshl_add_u64 v[28:29], v[28:29], 3, s[24:25]
	s_mov_b64 s[26:27], 0
	global_store_dwordx2 v[28:29], v[24:25], off
	global_store_dwordx2 v[28:29], v[26:27], off offset:256

; __device__ __forceinline__ unsigned cvt_pk_bf16(float lo, float hi) { unsigned r; asm volatile("v_cvt_pk_bf16_f32 %0, %1, %2" : "=v"(r) : "v"(lo), "v"(hi)); return r; }
;     __device__ __forceinline__ void operator()(const f32x4 (&acc)[2][2][4][2], const Unit& u, int wr, int wc, int fr, int fq) const {
;     ...
;             for (int m = 0; m < 4; ++m) { const int row = row0 + ai * HALF + m * 16;
;                 const float rs = __builtin_amdgcn_rsqf(ssq[row] * (1.0f / 1024.0f) + 1e-6f) * sc;
;                 const int b = row >> 12, tl = row & 4095, tile = tl >> 5, r = tl & 31;
; #pragma unroll
;                 for (int bj = 0; bj < 2; ++bj) { const int cc = (colt & 1023) + bj * HALF + wc * 32 + 8 * fq, h = cc >> 6, d8 = cc & 63, bh = b * 16 + h;
;                     const f32x4 v0 = acc[ai][bj][m][0] * rs, v1 = acc[ai][bj][m][1] * rs;
;                     u32x4 w; w.x = cvt_pk_bf16(v0[0], v0[1]); w.y = cvt_pk_bf16(v0[2], v0[3]); w.z = cvt_pk_bf16(v1[0], v1[1]); w.w = cvt_pk_bf16(v1[2], v1[3]);
;                     if (region < 2) { const int ks = d8 >> 4, hh = (d8 >> 3) & 1;
;                         *(u32x4*)(base + ((size_t)(((bh * 128 + tile) * 4 + ks) * 64 + hh * 32 + r) << 3)) = w;
;                     } else { const int dt = d8 >> 5, g = (d8 >> 3) & 3; bf16_t* p = base + ((size_t)((((bh * 128 + tile) * 2 + dt) * 4 + g) * 64 + r) << 2);
;                         *(unsigned long long*)p = (unsigned long long)w.x | ((unsigned long long)w.y << 32);
;                         *(unsigned long long*)(p + 128) = (unsigned long long)w.z | ((unsigned long long)w.w << 32); } }
.LBB0_549:
	s_nop 0
	s_nop 0
	v_add_u32_e32 v17, 0xb0, v144
	v_bfe_u32 v17, v17, 5, 7
	s_and_b64 vcc, exec, s[4:5]
	v_lshl_or_b32 v18, v17, 3, s69
	s_mov_b64 s[26:27], -1
	s_nop 0
	v_fmamk_f32 v16, v251, 0x3a800000, v165
	v_rsq_f32_e32 v16, v16
	s_nop 0
	v_mul_f32_e32 v16, v145, v16
	v_pk_mul_f32 v[20:21], v[10:11], v[16:17] op_sel_hi:[1,0]
	v_pk_mul_f32 v[10:11], v[8:9], v[16:17] op_sel_hi:[1,0]
	v_pk_mul_f32 v[14:15], v[14:15], v[16:17] op_sel_hi:[1,0]
	v_pk_mul_f32 v[12:13], v[12:13], v[16:17] op_sel_hi:[1,0]
	s_nop 0
	v_cvt_pk_bf16_f32 v8, v12, v13
	v_cvt_pk_bf16_f32 v9, v14, v15
	v_cvt_pk_bf16_f32 v10, v10, v11
	v_cvt_pk_bf16_f32 v11, v20, v21
	s_cbranch_vccnz .LBB0_551
	v_or3_b32 v12, v18, v61, v154
	v_lshl_or_b32 v12, v12, 6, v158
	v_ashrrev_i32_e32 v13, 31, v12
	v_lshl_add_u64 v[12:13], v[12:13], 3, s[24:25]
	s_mov_b64 s[26:27], 0
	global_store_dwordx2 v[12:13], v[8:9], off
	global_store_dwordx2 v[12:13], v[10:11], off offset:256
